# P0 hand-written norm item + GEMV unit, asynchronous queue pop; P6 FFN shift-bias rows spread over all workgroups
# speedup vs baseline: 1.0112x; 1.0112x over previous
.LBB0_1060:
	v_mov_b32_e32 v1, v0
	s_lshl_b32 s4, s2, 3
	v_readfirstlane_b32 s5, v1
	s_ashr_i32 s5, s5, 6
	s_add_i32 s4, s5, s4
	s_mov_b64 s[6:7], s[0:1]
	s_cmpk_gt_u32 s4, 0x15ff
	s_cbranch_scc1 .LBB0_1065
	s_load_dwordx2 s[6:7], s[6:7], 0xe0
	v_and_b32_e32 v1, 63, v1
	s_lshl_b32 s8, s33, 3
	v_mov_b32_e32 v3, 0
	v_lshlrev_b32_e32 v2, 5, v1
	s_waitcnt lgkmcnt(0)
	v_lshl_add_u64 v[4:5], s[6:7], 0, v[2:3]
	s_mov_b64 s[10:11], 0xd00000
	s_add_u32 s9, s6, 0x130000
	v_lshlrev_b32_e32 v2, 6, v1
	v_lshl_add_u64 v[4:5], v[4:5], 0, s[10:11]
	s_addc_u32 s10, s7, 0
	v_lshl_add_u64 v[8:9], s[6:7], 0, v[2:3]
	s_mov_b64 s[6:7], 0x13000
	v_lshl_add_u64 v[6:7], v[8:9], 0, s[6:7]
	s_mov_b64 s[6:7], 0x19000
	s_mov_b32 s5, 0
	v_cmp_eq_u32_e32 vcc, 0, v1
	v_lshl_add_u64 v[8:9], v[8:9], 0, s[6:7]
	v_mov_b32_e32 v1, 0x5000
	s_branch .LBB0_1063
